# S5 chunk-state combine: chunk-state loads issued 34 at a time ahead of the carry recurrence instead of one round trip per step
# baseline (speedup 1.0000x reference)
.LBB0_513:
	s_waitcnt lgkmcnt(0)
	s_mov_b32 s4, 0x0
	s_mov_b32 s5, 0
	v_lshl_add_u64 v[90:91], v[6:7], 0, s[4:5]
	s_mov_b32 s4, 0x1000
	s_mov_b32 s5, 0
	v_lshl_add_u64 v[92:93], v[6:7], 0, s[4:5]
	s_mov_b32 s4, 0x2000
	s_mov_b32 s5, 0
	v_lshl_add_u64 v[94:95], v[6:7], 0, s[4:5]
	s_mov_b32 s4, 0x3000
	s_mov_b32 s5, 0
	v_lshl_add_u64 v[96:97], v[6:7], 0, s[4:5]
	s_mov_b32 s4, 0x4000
	s_mov_b32 s5, 0
	v_lshl_add_u64 v[98:99], v[6:7], 0, s[4:5]
	global_load_dwordx2 v[20:21], v[90:91], off
	global_load_dwordx2 v[22:23], v[90:91], off offset:512
	global_load_dwordx2 v[24:25], v[90:91], off offset:1024
	global_load_dwordx2 v[26:27], v[90:91], off offset:1536
	global_load_dwordx2 v[28:29], v[90:91], off offset:2048
	global_load_dwordx2 v[30:31], v[90:91], off offset:2560
	global_load_dwordx2 v[32:33], v[90:91], off offset:3072
	global_load_dwordx2 v[34:35], v[90:91], off offset:3584
	global_load_dwordx2 v[36:37], v[92:93], off
	global_load_dwordx2 v[38:39], v[92:93], off offset:512
	global_load_dwordx2 v[40:41], v[92:93], off offset:1024
	global_load_dwordx2 v[42:43], v[92:93], off offset:1536
	global_load_dwordx2 v[44:45], v[92:93], off offset:2048
	global_load_dwordx2 v[46:47], v[92:93], off offset:2560
	global_load_dwordx2 v[48:49], v[92:93], off offset:3072
	global_load_dwordx2 v[50:51], v[92:93], off offset:3584
	global_load_dwordx2 v[52:53], v[94:95], off
	global_load_dwordx2 v[54:55], v[94:95], off offset:512
	global_load_dwordx2 v[56:57], v[94:95], off offset:1024
	global_load_dwordx2 v[58:59], v[94:95], off offset:1536
	global_load_dwordx2 v[60:61], v[94:95], off offset:2048
	global_load_dwordx2 v[62:63], v[94:95], off offset:2560
	global_load_dwordx2 v[64:65], v[94:95], off offset:3072
	global_load_dwordx2 v[66:67], v[94:95], off offset:3584
	global_load_dwordx2 v[68:69], v[96:97], off
	global_load_dwordx2 v[70:71], v[96:97], off offset:512
	global_load_dwordx2 v[72:73], v[96:97], off offset:1024
	global_load_dwordx2 v[74:75], v[96:97], off offset:1536
	global_load_dwordx2 v[76:77], v[96:97], off offset:2048
	global_load_dwordx2 v[78:79], v[96:97], off offset:2560
	global_load_dwordx2 v[80:81], v[96:97], off offset:3072
	global_load_dwordx2 v[82:83], v[96:97], off offset:3584
	global_load_dwordx2 v[84:85], v[98:99], off
	global_load_dwordx2 v[86:87], v[98:99], off offset:512
	s_nop 0
	v_pk_mul_f32 v[12:13], v[4:5], v[8:9] op_sel:[0,1] op_sel_hi:[1,0]
	global_store_dwordx2 v[90:91], v[8:9], off
	v_pk_fma_f32 v[16:17], v[2:3], v[8:9], v[12:13] neg_lo:[0,0,1] neg_hi:[0,0,1]
	v_pk_fma_f32 v[8:9], v[2:3], v[8:9], v[12:13]
	s_nop 0
	v_mov_b32_e32 v17, v9
	s_waitcnt vmcnt(34)
	v_pk_add_f32 v[8:9], v[16:17], v[20:21]
	s_nop 0
	v_pk_mul_f32 v[12:13], v[4:5], v[8:9] op_sel:[0,1] op_sel_hi:[1,0]
	global_store_dwordx2 v[90:91], v[8:9], off offset:512
	v_pk_fma_f32 v[16:17], v[2:3], v[8:9], v[12:13] neg_lo:[0,0,1] neg_hi:[0,0,1]
	v_pk_fma_f32 v[8:9], v[2:3], v[8:9], v[12:13]
	s_nop 0
	v_mov_b32_e32 v17, v9
	s_waitcnt vmcnt(34)
	v_pk_add_f32 v[8:9], v[16:17], v[22:23]
	s_nop 0
	v_pk_mul_f32 v[12:13], v[4:5], v[8:9] op_sel:[0,1] op_sel_hi:[1,0]
	global_store_dwordx2 v[90:91], v[8:9], off offset:1024
	v_pk_fma_f32 v[16:17], v[2:3], v[8:9], v[12:13] neg_lo:[0,0,1] neg_hi:[0,0,1]
	v_pk_fma_f32 v[8:9], v[2:3], v[8:9], v[12:13]
	s_nop 0
	v_mov_b32_e32 v17, v9
	s_waitcnt vmcnt(34)
	v_pk_add_f32 v[8:9], v[16:17], v[24:25]
	s_nop 0
	v_pk_mul_f32 v[12:13], v[4:5], v[8:9] op_sel:[0,1] op_sel_hi:[1,0]
	global_store_dwordx2 v[90:91], v[8:9], off offset:1536
	v_pk_fma_f32 v[16:17], v[2:3], v[8:9], v[12:13] neg_lo:[0,0,1] neg_hi:[0,0,1]
	v_pk_fma_f32 v[8:9], v[2:3], v[8:9], v[12:13]
	s_nop 0
	v_mov_b32_e32 v17, v9
	s_waitcnt vmcnt(34)
	v_pk_add_f32 v[8:9], v[16:17], v[26:27]
	s_nop 0
	v_pk_mul_f32 v[12:13], v[4:5], v[8:9] op_sel:[0,1] op_sel_hi:[1,0]
	global_store_dwordx2 v[90:91], v[8:9], off offset:2048
	v_pk_fma_f32 v[16:17], v[2:3], v[8:9], v[12:13] neg_lo:[0,0,1] neg_hi:[0,0,1]
	v_pk_fma_f32 v[8:9], v[2:3], v[8:9], v[12:13]
	s_nop 0
	v_mov_b32_e32 v17, v9
	s_waitcnt vmcnt(34)
	v_pk_add_f32 v[8:9], v[16:17], v[28:29]
	s_nop 0
	v_pk_mul_f32 v[12:13], v[4:5], v[8:9] op_sel:[0,1] op_sel_hi:[1,0]
	global_store_dwordx2 v[90:91], v[8:9], off offset:2560
	v_pk_fma_f32 v[16:17], v[2:3], v[8:9], v[12:13] neg_lo:[0,0,1] neg_hi:[0,0,1]
	v_pk_fma_f32 v[8:9], v[2:3], v[8:9], v[12:13]
	s_nop 0
	v_mov_b32_e32 v17, v9
	s_waitcnt vmcnt(34)
	v_pk_add_f32 v[8:9], v[16:17], v[30:31]
	s_nop 0
	v_pk_mul_f32 v[12:13], v[4:5], v[8:9] op_sel:[0,1] op_sel_hi:[1,0]
	global_store_dwordx2 v[90:91], v[8:9], off offset:3072
	v_pk_fma_f32 v[16:17], v[2:3], v[8:9], v[12:13] neg_lo:[0,0,1] neg_hi:[0,0,1]
	v_pk_fma_f32 v[8:9], v[2:3], v[8:9], v[12:13]
	s_nop 0
	v_mov_b32_e32 v17, v9
	s_waitcnt vmcnt(34)
	v_pk_add_f32 v[8:9], v[16:17], v[32:33]
	s_nop 0
	v_pk_mul_f32 v[12:13], v[4:5], v[8:9] op_sel:[0,1] op_sel_hi:[1,0]
	global_store_dwordx2 v[90:91], v[8:9], off offset:3584
	v_pk_fma_f32 v[16:17], v[2:3], v[8:9], v[12:13] neg_lo:[0,0,1] neg_hi:[0,0,1]
	v_pk_fma_f32 v[8:9], v[2:3], v[8:9], v[12:13]
	s_nop 0
	v_mov_b32_e32 v17, v9
	s_waitcnt vmcnt(34)
	v_pk_add_f32 v[8:9], v[16:17], v[34:35]
	s_nop 0
	v_pk_mul_f32 v[12:13], v[4:5], v[8:9] op_sel:[0,1] op_sel_hi:[1,0]
	global_store_dwordx2 v[92:93], v[8:9], off
	v_pk_fma_f32 v[16:17], v[2:3], v[8:9], v[12:13] neg_lo:[0,0,1] neg_hi:[0,0,1]
	v_pk_fma_f32 v[8:9], v[2:3], v[8:9], v[12:13]
	s_nop 0
	v_mov_b32_e32 v17, v9
	s_waitcnt vmcnt(34)
	v_pk_add_f32 v[8:9], v[16:17], v[36:37]
	s_nop 0
	v_pk_mul_f32 v[12:13], v[4:5], v[8:9] op_sel:[0,1] op_sel_hi:[1,0]
	global_store_dwordx2 v[92:93], v[8:9], off offset:512
	v_pk_fma_f32 v[16:17], v[2:3], v[8:9], v[12:13] neg_lo:[0,0,1] neg_hi:[0,0,1]
	v_pk_fma_f32 v[8:9], v[2:3], v[8:9], v[12:13]
	s_nop 0
	v_mov_b32_e32 v17, v9
	s_waitcnt vmcnt(34)
	v_pk_add_f32 v[8:9], v[16:17], v[38:39]
	s_nop 0
	v_pk_mul_f32 v[12:13], v[4:5], v[8:9] op_sel:[0,1] op_sel_hi:[1,0]
	global_store_dwordx2 v[92:93], v[8:9], off offset:1024
	v_pk_fma_f32 v[16:17], v[2:3], v[8:9], v[12:13] neg_lo:[0,0,1] neg_hi:[0,0,1]
	v_pk_fma_f32 v[8:9], v[2:3], v[8:9], v[12:13]
	s_nop 0
	v_mov_b32_e32 v17, v9
	s_waitcnt vmcnt(34)
	v_pk_add_f32 v[8:9], v[16:17], v[40:41]
	s_nop 0
	v_pk_mul_f32 v[12:13], v[4:5], v[8:9] op_sel:[0,1] op_sel_hi:[1,0]
	global_store_dwordx2 v[92:93], v[8:9], off offset:1536
	v_pk_fma_f32 v[16:17], v[2:3], v[8:9], v[12:13] neg_lo:[0,0,1] neg_hi:[0,0,1]
	v_pk_fma_f32 v[8:9], v[2:3], v[8:9], v[12:13]
	s_nop 0
	v_mov_b32_e32 v17, v9
	s_waitcnt vmcnt(34)
	v_pk_add_f32 v[8:9], v[16:17], v[42:43]
	s_nop 0
	v_pk_mul_f32 v[12:13], v[4:5], v[8:9] op_sel:[0,1] op_sel_hi:[1,0]
	global_store_dwordx2 v[92:93], v[8:9], off offset:2048
	v_pk_fma_f32 v[16:17], v[2:3], v[8:9], v[12:13] neg_lo:[0,0,1] neg_hi:[0,0,1]
	v_pk_fma_f32 v[8:9], v[2:3], v[8:9], v[12:13]
	s_nop 0
	v_mov_b32_e32 v17, v9
	s_waitcnt vmcnt(34)
	v_pk_add_f32 v[8:9], v[16:17], v[44:45]
	s_nop 0
	v_pk_mul_f32 v[12:13], v[4:5], v[8:9] op_sel:[0,1] op_sel_hi:[1,0]
	global_store_dwordx2 v[92:93], v[8:9], off offset:2560
	v_pk_fma_f32 v[16:17], v[2:3], v[8:9], v[12:13] neg_lo:[0,0,1] neg_hi:[0,0,1]
	v_pk_fma_f32 v[8:9], v[2:3], v[8:9], v[12:13]
	s_nop 0
	v_mov_b32_e32 v17, v9
	s_waitcnt vmcnt(34)
	v_pk_add_f32 v[8:9], v[16:17], v[46:47]
	s_nop 0
	v_pk_mul_f32 v[12:13], v[4:5], v[8:9] op_sel:[0,1] op_sel_hi:[1,0]
	global_store_dwordx2 v[92:93], v[8:9], off offset:3072
	v_pk_fma_f32 v[16:17], v[2:3], v[8:9], v[12:13] neg_lo:[0,0,1] neg_hi:[0,0,1]
	v_pk_fma_f32 v[8:9], v[2:3], v[8:9], v[12:13]
	s_nop 0
	v_mov_b32_e32 v17, v9
	s_waitcnt vmcnt(34)
	v_pk_add_f32 v[8:9], v[16:17], v[48:49]
	s_nop 0
	v_pk_mul_f32 v[12:13], v[4:5], v[8:9] op_sel:[0,1] op_sel_hi:[1,0]
	global_store_dwordx2 v[92:93], v[8:9], off offset:3584
	v_pk_fma_f32 v[16:17], v[2:3], v[8:9], v[12:13] neg_lo:[0,0,1] neg_hi:[0,0,1]
	v_pk_fma_f32 v[8:9], v[2:3], v[8:9], v[12:13]
	s_nop 0
	v_mov_b32_e32 v17, v9
	s_waitcnt vmcnt(34)
	v_pk_add_f32 v[8:9], v[16:17], v[50:51]
	s_nop 0
	v_pk_mul_f32 v[12:13], v[4:5], v[8:9] op_sel:[0,1] op_sel_hi:[1,0]
	global_store_dwordx2 v[94:95], v[8:9], off
	v_pk_fma_f32 v[16:17], v[2:3], v[8:9], v[12:13] neg_lo:[0,0,1] neg_hi:[0,0,1]
	v_pk_fma_f32 v[8:9], v[2:3], v[8:9], v[12:13]
	s_nop 0
	v_mov_b32_e32 v17, v9
	s_waitcnt vmcnt(34)
	v_pk_add_f32 v[8:9], v[16:17], v[52:53]
	s_nop 0
	v_pk_mul_f32 v[12:13], v[4:5], v[8:9] op_sel:[0,1] op_sel_hi:[1,0]
	global_store_dwordx2 v[94:95], v[8:9], off offset:512
	v_pk_fma_f32 v[16:17], v[2:3], v[8:9], v[12:13] neg_lo:[0,0,1] neg_hi:[0,0,1]
	v_pk_fma_f32 v[8:9], v[2:3], v[8:9], v[12:13]
	s_nop 0
	v_mov_b32_e32 v17, v9
	s_waitcnt vmcnt(34)
	v_pk_add_f32 v[8:9], v[16:17], v[54:55]
	s_nop 0
	v_pk_mul_f32 v[12:13], v[4:5], v[8:9] op_sel:[0,1] op_sel_hi:[1,0]
	global_store_dwordx2 v[94:95], v[8:9], off offset:1024
	v_pk_fma_f32 v[16:17], v[2:3], v[8:9], v[12:13] neg_lo:[0,0,1] neg_hi:[0,0,1]
	v_pk_fma_f32 v[8:9], v[2:3], v[8:9], v[12:13]
	s_nop 0
	v_mov_b32_e32 v17, v9
	s_waitcnt vmcnt(34)
	v_pk_add_f32 v[8:9], v[16:17], v[56:57]
	s_nop 0
	v_pk_mul_f32 v[12:13], v[4:5], v[8:9] op_sel:[0,1] op_sel_hi:[1,0]
	global_store_dwordx2 v[94:95], v[8:9], off offset:1536
	v_pk_fma_f32 v[16:17], v[2:3], v[8:9], v[12:13] neg_lo:[0,0,1] neg_hi:[0,0,1]
	v_pk_fma_f32 v[8:9], v[2:3], v[8:9], v[12:13]
	s_nop 0
	v_mov_b32_e32 v17, v9
	s_waitcnt vmcnt(34)
	v_pk_add_f32 v[8:9], v[16:17], v[58:59]
	s_nop 0
	v_pk_mul_f32 v[12:13], v[4:5], v[8:9] op_sel:[0,1] op_sel_hi:[1,0]
	global_store_dwordx2 v[94:95], v[8:9], off offset:2048
	v_pk_fma_f32 v[16:17], v[2:3], v[8:9], v[12:13] neg_lo:[0,0,1] neg_hi:[0,0,1]
	v_pk_fma_f32 v[8:9], v[2:3], v[8:9], v[12:13]
	s_nop 0
	v_mov_b32_e32 v17, v9
	s_waitcnt vmcnt(34)
	v_pk_add_f32 v[8:9], v[16:17], v[60:61]
	s_nop 0
	v_pk_mul_f32 v[12:13], v[4:5], v[8:9] op_sel:[0,1] op_sel_hi:[1,0]
	global_store_dwordx2 v[94:95], v[8:9], off offset:2560
	v_pk_fma_f32 v[16:17], v[2:3], v[8:9], v[12:13] neg_lo:[0,0,1] neg_hi:[0,0,1]
	v_pk_fma_f32 v[8:9], v[2:3], v[8:9], v[12:13]
	s_nop 0
	v_mov_b32_e32 v17, v9
	s_waitcnt vmcnt(34)
	v_pk_add_f32 v[8:9], v[16:17], v[62:63]
	s_nop 0
	v_pk_mul_f32 v[12:13], v[4:5], v[8:9] op_sel:[0,1] op_sel_hi:[1,0]
	global_store_dwordx2 v[94:95], v[8:9], off offset:3072
	v_pk_fma_f32 v[16:17], v[2:3], v[8:9], v[12:13] neg_lo:[0,0,1] neg_hi:[0,0,1]
	v_pk_fma_f32 v[8:9], v[2:3], v[8:9], v[12:13]
	s_nop 0
	v_mov_b32_e32 v17, v9
	s_waitcnt vmcnt(34)
	v_pk_add_f32 v[8:9], v[16:17], v[64:65]
	s_nop 0
	v_pk_mul_f32 v[12:13], v[4:5], v[8:9] op_sel:[0,1] op_sel_hi:[1,0]
	global_store_dwordx2 v[94:95], v[8:9], off offset:3584
	v_pk_fma_f32 v[16:17], v[2:3], v[8:9], v[12:13] neg_lo:[0,0,1] neg_hi:[0,0,1]
	v_pk_fma_f32 v[8:9], v[2:3], v[8:9], v[12:13]
	s_nop 0
	v_mov_b32_e32 v17, v9
	s_waitcnt vmcnt(34)
	v_pk_add_f32 v[8:9], v[16:17], v[66:67]
	s_nop 0
	v_pk_mul_f32 v[12:13], v[4:5], v[8:9] op_sel:[0,1] op_sel_hi:[1,0]
	global_store_dwordx2 v[96:97], v[8:9], off
	v_pk_fma_f32 v[16:17], v[2:3], v[8:9], v[12:13] neg_lo:[0,0,1] neg_hi:[0,0,1]
	v_pk_fma_f32 v[8:9], v[2:3], v[8:9], v[12:13]
	s_nop 0
	v_mov_b32_e32 v17, v9
	s_waitcnt vmcnt(34)
	v_pk_add_f32 v[8:9], v[16:17], v[68:69]
	s_nop 0
	v_pk_mul_f32 v[12:13], v[4:5], v[8:9] op_sel:[0,1] op_sel_hi:[1,0]
	global_store_dwordx2 v[96:97], v[8:9], off offset:512
	v_pk_fma_f32 v[16:17], v[2:3], v[8:9], v[12:13] neg_lo:[0,0,1] neg_hi:[0,0,1]
	v_pk_fma_f32 v[8:9], v[2:3], v[8:9], v[12:13]
	s_nop 0
	v_mov_b32_e32 v17, v9
	s_waitcnt vmcnt(34)
	v_pk_add_f32 v[8:9], v[16:17], v[70:71]
	s_nop 0
	v_pk_mul_f32 v[12:13], v[4:5], v[8:9] op_sel:[0,1] op_sel_hi:[1,0]
	global_store_dwordx2 v[96:97], v[8:9], off offset:1024
	v_pk_fma_f32 v[16:17], v[2:3], v[8:9], v[12:13] neg_lo:[0,0,1] neg_hi:[0,0,1]
	v_pk_fma_f32 v[8:9], v[2:3], v[8:9], v[12:13]
	s_nop 0
	v_mov_b32_e32 v17, v9
	s_waitcnt vmcnt(34)
	v_pk_add_f32 v[8:9], v[16:17], v[72:73]
	s_nop 0
	v_pk_mul_f32 v[12:13], v[4:5], v[8:9] op_sel:[0,1] op_sel_hi:[1,0]
	global_store_dwordx2 v[96:97], v[8:9], off offset:1536
	v_pk_fma_f32 v[16:17], v[2:3], v[8:9], v[12:13] neg_lo:[0,0,1] neg_hi:[0,0,1]
	v_pk_fma_f32 v[8:9], v[2:3], v[8:9], v[12:13]
	s_nop 0
	v_mov_b32_e32 v17, v9
	s_waitcnt vmcnt(34)
	v_pk_add_f32 v[8:9], v[16:17], v[74:75]
	s_nop 0
	v_pk_mul_f32 v[12:13], v[4:5], v[8:9] op_sel:[0,1] op_sel_hi:[1,0]
	global_store_dwordx2 v[96:97], v[8:9], off offset:2048
	v_pk_fma_f32 v[16:17], v[2:3], v[8:9], v[12:13] neg_lo:[0,0,1] neg_hi:[0,0,1]
	v_pk_fma_f32 v[8:9], v[2:3], v[8:9], v[12:13]
	s_nop 0
	v_mov_b32_e32 v17, v9
	s_waitcnt vmcnt(34)
	v_pk_add_f32 v[8:9], v[16:17], v[76:77]
	s_nop 0
	v_pk_mul_f32 v[12:13], v[4:5], v[8:9] op_sel:[0,1] op_sel_hi:[1,0]
	global_store_dwordx2 v[96:97], v[8:9], off offset:2560
	v_pk_fma_f32 v[16:17], v[2:3], v[8:9], v[12:13] neg_lo:[0,0,1] neg_hi:[0,0,1]
	v_pk_fma_f32 v[8:9], v[2:3], v[8:9], v[12:13]
	s_nop 0
	v_mov_b32_e32 v17, v9
	s_waitcnt vmcnt(34)
	v_pk_add_f32 v[8:9], v[16:17], v[78:79]
	s_nop 0
	v_pk_mul_f32 v[12:13], v[4:5], v[8:9] op_sel:[0,1] op_sel_hi:[1,0]
	global_store_dwordx2 v[96:97], v[8:9], off offset:3072
	v_pk_fma_f32 v[16:17], v[2:3], v[8:9], v[12:13] neg_lo:[0,0,1] neg_hi:[0,0,1]
	v_pk_fma_f32 v[8:9], v[2:3], v[8:9], v[12:13]
	s_nop 0
	v_mov_b32_e32 v17, v9
	s_waitcnt vmcnt(34)
	v_pk_add_f32 v[8:9], v[16:17], v[80:81]
	s_nop 0
	v_pk_mul_f32 v[12:13], v[4:5], v[8:9] op_sel:[0,1] op_sel_hi:[1,0]
	global_store_dwordx2 v[96:97], v[8:9], off offset:3584
	v_pk_fma_f32 v[16:17], v[2:3], v[8:9], v[12:13] neg_lo:[0,0,1] neg_hi:[0,0,1]
	v_pk_fma_f32 v[8:9], v[2:3], v[8:9], v[12:13]
	s_nop 0
	v_mov_b32_e32 v17, v9
	s_waitcnt vmcnt(34)
	v_pk_add_f32 v[8:9], v[16:17], v[82:83]
	s_nop 0
	v_pk_mul_f32 v[12:13], v[4:5], v[8:9] op_sel:[0,1] op_sel_hi:[1,0]
	global_store_dwordx2 v[98:99], v[8:9], off
	v_pk_fma_f32 v[16:17], v[2:3], v[8:9], v[12:13] neg_lo:[0,0,1] neg_hi:[0,0,1]
	v_pk_fma_f32 v[8:9], v[2:3], v[8:9], v[12:13]
	s_nop 0
	v_mov_b32_e32 v17, v9
	s_waitcnt vmcnt(34)
	v_pk_add_f32 v[8:9], v[16:17], v[84:85]
	s_nop 0
	v_pk_mul_f32 v[12:13], v[4:5], v[8:9] op_sel:[0,1] op_sel_hi:[1,0]
	global_store_dwordx2 v[98:99], v[8:9], off offset:512
	v_pk_fma_f32 v[16:17], v[2:3], v[8:9], v[12:13] neg_lo:[0,0,1] neg_hi:[0,0,1]
	v_pk_fma_f32 v[8:9], v[2:3], v[8:9], v[12:13]
	s_nop 0
	v_mov_b32_e32 v17, v9
	s_waitcnt vmcnt(34)
	v_pk_add_f32 v[8:9], v[16:17], v[86:87]
	s_mov_b32 s4, 0x4400
	s_mov_b32 s5, 0
	v_lshl_add_u64 v[90:91], v[6:7], 0, s[4:5]
	s_mov_b32 s4, 0x5400
	s_mov_b32 s5, 0
	v_lshl_add_u64 v[92:93], v[6:7], 0, s[4:5]
	s_mov_b32 s4, 0x6400
	s_mov_b32 s5, 0
	v_lshl_add_u64 v[94:95], v[6:7], 0, s[4:5]
	s_mov_b32 s4, 0x7400
	s_mov_b32 s5, 0
	v_lshl_add_u64 v[96:97], v[6:7], 0, s[4:5]
	s_mov_b32 s4, 0x8400
	s_mov_b32 s5, 0
	v_lshl_add_u64 v[98:99], v[6:7], 0, s[4:5]
	global_load_dwordx2 v[20:21], v[90:91], off
	global_load_dwordx2 v[22:23], v[90:91], off offset:512
	global_load_dwordx2 v[24:25], v[90:91], off offset:1024
	global_load_dwordx2 v[26:27], v[90:91], off offset:1536
	global_load_dwordx2 v[28:29], v[90:91], off offset:2048
	global_load_dwordx2 v[30:31], v[90:91], off offset:2560
	global_load_dwordx2 v[32:33], v[90:91], off offset:3072
	global_load_dwordx2 v[34:35], v[90:91], off offset:3584
	global_load_dwordx2 v[36:37], v[92:93], off
	global_load_dwordx2 v[38:39], v[92:93], off offset:512
	global_load_dwordx2 v[40:41], v[92:93], off offset:1024
	global_load_dwordx2 v[42:43], v[92:93], off offset:1536
	global_load_dwordx2 v[44:45], v[92:93], off offset:2048
	global_load_dwordx2 v[46:47], v[92:93], off offset:2560
	global_load_dwordx2 v[48:49], v[92:93], off offset:3072
	global_load_dwordx2 v[50:51], v[92:93], off offset:3584
	global_load_dwordx2 v[52:53], v[94:95], off
	global_load_dwordx2 v[54:55], v[94:95], off offset:512
	global_load_dwordx2 v[56:57], v[94:95], off offset:1024
	global_load_dwordx2 v[58:59], v[94:95], off offset:1536
	global_load_dwordx2 v[60:61], v[94:95], off offset:2048
	global_load_dwordx2 v[62:63], v[94:95], off offset:2560
	global_load_dwordx2 v[64:65], v[94:95], off offset:3072
	global_load_dwordx2 v[66:67], v[94:95], off offset:3584
	global_load_dwordx2 v[68:69], v[96:97], off
	global_load_dwordx2 v[70:71], v[96:97], off offset:512
	global_load_dwordx2 v[72:73], v[96:97], off offset:1024
	global_load_dwordx2 v[74:75], v[96:97], off offset:1536
	global_load_dwordx2 v[76:77], v[96:97], off offset:2048
	global_load_dwordx2 v[78:79], v[96:97], off offset:2560
	global_load_dwordx2 v[80:81], v[96:97], off offset:3072
	global_load_dwordx2 v[82:83], v[96:97], off offset:3584
	global_load_dwordx2 v[84:85], v[98:99], off
	global_load_dwordx2 v[86:87], v[98:99], off offset:512
	s_nop 0
	v_pk_mul_f32 v[12:13], v[4:5], v[8:9] op_sel:[0,1] op_sel_hi:[1,0]
	global_store_dwordx2 v[90:91], v[8:9], off
	v_pk_fma_f32 v[16:17], v[2:3], v[8:9], v[12:13] neg_lo:[0,0,1] neg_hi:[0,0,1]
	v_pk_fma_f32 v[8:9], v[2:3], v[8:9], v[12:13]
	s_nop 0
	v_mov_b32_e32 v17, v9
	s_waitcnt vmcnt(34)
	v_pk_add_f32 v[8:9], v[16:17], v[20:21]
	s_nop 0
	v_pk_mul_f32 v[12:13], v[4:5], v[8:9] op_sel:[0,1] op_sel_hi:[1,0]
	global_store_dwordx2 v[90:91], v[8:9], off offset:512
	v_pk_fma_f32 v[16:17], v[2:3], v[8:9], v[12:13] neg_lo:[0,0,1] neg_hi:[0,0,1]
	v_pk_fma_f32 v[8:9], v[2:3], v[8:9], v[12:13]
	s_nop 0
	v_mov_b32_e32 v17, v9
	s_waitcnt vmcnt(34)
	v_pk_add_f32 v[8:9], v[16:17], v[22:23]
	s_nop 0
	v_pk_mul_f32 v[12:13], v[4:5], v[8:9] op_sel:[0,1] op_sel_hi:[1,0]
	global_store_dwordx2 v[90:91], v[8:9], off offset:1024
	v_pk_fma_f32 v[16:17], v[2:3], v[8:9], v[12:13] neg_lo:[0,0,1] neg_hi:[0,0,1]
	v_pk_fma_f32 v[8:9], v[2:3], v[8:9], v[12:13]
	s_nop 0
	v_mov_b32_e32 v17, v9
	s_waitcnt vmcnt(34)
	v_pk_add_f32 v[8:9], v[16:17], v[24:25]
	s_nop 0
	v_pk_mul_f32 v[12:13], v[4:5], v[8:9] op_sel:[0,1] op_sel_hi:[1,0]
	global_store_dwordx2 v[90:91], v[8:9], off offset:1536
	v_pk_fma_f32 v[16:17], v[2:3], v[8:9], v[12:13] neg_lo:[0,0,1] neg_hi:[0,0,1]
	v_pk_fma_f32 v[8:9], v[2:3], v[8:9], v[12:13]
	s_nop 0
	v_mov_b32_e32 v17, v9
	s_waitcnt vmcnt(34)
	v_pk_add_f32 v[8:9], v[16:17], v[26:27]
	s_nop 0
	v_pk_mul_f32 v[12:13], v[4:5], v[8:9] op_sel:[0,1] op_sel_hi:[1,0]
	global_store_dwordx2 v[90:91], v[8:9], off offset:2048
	v_pk_fma_f32 v[16:17], v[2:3], v[8:9], v[12:13] neg_lo:[0,0,1] neg_hi:[0,0,1]
	v_pk_fma_f32 v[8:9], v[2:3], v[8:9], v[12:13]
	s_nop 0
	v_mov_b32_e32 v17, v9
	s_waitcnt vmcnt(34)
	v_pk_add_f32 v[8:9], v[16:17], v[28:29]
	s_nop 0
	v_pk_mul_f32 v[12:13], v[4:5], v[8:9] op_sel:[0,1] op_sel_hi:[1,0]
	global_store_dwordx2 v[90:91], v[8:9], off offset:2560
	v_pk_fma_f32 v[16:17], v[2:3], v[8:9], v[12:13] neg_lo:[0,0,1] neg_hi:[0,0,1]
	v_pk_fma_f32 v[8:9], v[2:3], v[8:9], v[12:13]
	s_nop 0
	v_mov_b32_e32 v17, v9
	s_waitcnt vmcnt(34)
	v_pk_add_f32 v[8:9], v[16:17], v[30:31]
	s_nop 0
	v_pk_mul_f32 v[12:13], v[4:5], v[8:9] op_sel:[0,1] op_sel_hi:[1,0]
	global_store_dwordx2 v[90:91], v[8:9], off offset:3072
	v_pk_fma_f32 v[16:17], v[2:3], v[8:9], v[12:13] neg_lo:[0,0,1] neg_hi:[0,0,1]
	v_pk_fma_f32 v[8:9], v[2:3], v[8:9], v[12:13]
	s_nop 0
	v_mov_b32_e32 v17, v9
	s_waitcnt vmcnt(34)
	v_pk_add_f32 v[8:9], v[16:17], v[32:33]
	s_nop 0
	v_pk_mul_f32 v[12:13], v[4:5], v[8:9] op_sel:[0,1] op_sel_hi:[1,0]
	global_store_dwordx2 v[90:91], v[8:9], off offset:3584
	v_pk_fma_f32 v[16:17], v[2:3], v[8:9], v[12:13] neg_lo:[0,0,1] neg_hi:[0,0,1]
	v_pk_fma_f32 v[8:9], v[2:3], v[8:9], v[12:13]
	s_nop 0
	v_mov_b32_e32 v17, v9
	s_waitcnt vmcnt(34)
	v_pk_add_f32 v[8:9], v[16:17], v[34:35]
	s_nop 0
	v_pk_mul_f32 v[12:13], v[4:5], v[8:9] op_sel:[0,1] op_sel_hi:[1,0]
	global_store_dwordx2 v[92:93], v[8:9], off
	v_pk_fma_f32 v[16:17], v[2:3], v[8:9], v[12:13] neg_lo:[0,0,1] neg_hi:[0,0,1]
	v_pk_fma_f32 v[8:9], v[2:3], v[8:9], v[12:13]
	s_nop 0
	v_mov_b32_e32 v17, v9
	s_waitcnt vmcnt(34)
	v_pk_add_f32 v[8:9], v[16:17], v[36:37]
	s_nop 0
	v_pk_mul_f32 v[12:13], v[4:5], v[8:9] op_sel:[0,1] op_sel_hi:[1,0]
	global_store_dwordx2 v[92:93], v[8:9], off offset:512
	v_pk_fma_f32 v[16:17], v[2:3], v[8:9], v[12:13] neg_lo:[0,0,1] neg_hi:[0,0,1]
	v_pk_fma_f32 v[8:9], v[2:3], v[8:9], v[12:13]
	s_nop 0
	v_mov_b32_e32 v17, v9
	s_waitcnt vmcnt(34)
	v_pk_add_f32 v[8:9], v[16:17], v[38:39]
	s_nop 0
	v_pk_mul_f32 v[12:13], v[4:5], v[8:9] op_sel:[0,1] op_sel_hi:[1,0]
	global_store_dwordx2 v[92:93], v[8:9], off offset:1024
	v_pk_fma_f32 v[16:17], v[2:3], v[8:9], v[12:13] neg_lo:[0,0,1] neg_hi:[0,0,1]
	v_pk_fma_f32 v[8:9], v[2:3], v[8:9], v[12:13]
	s_nop 0
	v_mov_b32_e32 v17, v9
	s_waitcnt vmcnt(34)
	v_pk_add_f32 v[8:9], v[16:17], v[40:41]
	s_nop 0
	v_pk_mul_f32 v[12:13], v[4:5], v[8:9] op_sel:[0,1] op_sel_hi:[1,0]
	global_store_dwordx2 v[92:93], v[8:9], off offset:1536
	v_pk_fma_f32 v[16:17], v[2:3], v[8:9], v[12:13] neg_lo:[0,0,1] neg_hi:[0,0,1]
	v_pk_fma_f32 v[8:9], v[2:3], v[8:9], v[12:13]
	s_nop 0
	v_mov_b32_e32 v17, v9
	s_waitcnt vmcnt(34)
	v_pk_add_f32 v[8:9], v[16:17], v[42:43]
	s_nop 0
	v_pk_mul_f32 v[12:13], v[4:5], v[8:9] op_sel:[0,1] op_sel_hi:[1,0]
	global_store_dwordx2 v[92:93], v[8:9], off offset:2048
	v_pk_fma_f32 v[16:17], v[2:3], v[8:9], v[12:13] neg_lo:[0,0,1] neg_hi:[0,0,1]
	v_pk_fma_f32 v[8:9], v[2:3], v[8:9], v[12:13]
	s_nop 0
	v_mov_b32_e32 v17, v9
	s_waitcnt vmcnt(34)
	v_pk_add_f32 v[8:9], v[16:17], v[44:45]
	s_nop 0
	v_pk_mul_f32 v[12:13], v[4:5], v[8:9] op_sel:[0,1] op_sel_hi:[1,0]
	global_store_dwordx2 v[92:93], v[8:9], off offset:2560
	v_pk_fma_f32 v[16:17], v[2:3], v[8:9], v[12:13] neg_lo:[0,0,1] neg_hi:[0,0,1]
	v_pk_fma_f32 v[8:9], v[2:3], v[8:9], v[12:13]
	s_nop 0
	v_mov_b32_e32 v17, v9
	s_waitcnt vmcnt(34)
	v_pk_add_f32 v[8:9], v[16:17], v[46:47]
	s_nop 0
	v_pk_mul_f32 v[12:13], v[4:5], v[8:9] op_sel:[0,1] op_sel_hi:[1,0]
	global_store_dwordx2 v[92:93], v[8:9], off offset:3072
	v_pk_fma_f32 v[16:17], v[2:3], v[8:9], v[12:13] neg_lo:[0,0,1] neg_hi:[0,0,1]
	v_pk_fma_f32 v[8:9], v[2:3], v[8:9], v[12:13]
	s_nop 0
	v_mov_b32_e32 v17, v9
	s_waitcnt vmcnt(34)
	v_pk_add_f32 v[8:9], v[16:17], v[48:49]
	s_nop 0
	v_pk_mul_f32 v[12:13], v[4:5], v[8:9] op_sel:[0,1] op_sel_hi:[1,0]
	global_store_dwordx2 v[92:93], v[8:9], off offset:3584
	v_pk_fma_f32 v[16:17], v[2:3], v[8:9], v[12:13] neg_lo:[0,0,1] neg_hi:[0,0,1]
	v_pk_fma_f32 v[8:9], v[2:3], v[8:9], v[12:13]
	s_nop 0
	v_mov_b32_e32 v17, v9
	s_waitcnt vmcnt(34)
	v_pk_add_f32 v[8:9], v[16:17], v[50:51]
	s_nop 0
	v_pk_mul_f32 v[12:13], v[4:5], v[8:9] op_sel:[0,1] op_sel_hi:[1,0]
	global_store_dwordx2 v[94:95], v[8:9], off
	v_pk_fma_f32 v[16:17], v[2:3], v[8:9], v[12:13] neg_lo:[0,0,1] neg_hi:[0,0,1]
	v_pk_fma_f32 v[8:9], v[2:3], v[8:9], v[12:13]
	s_nop 0
	v_mov_b32_e32 v17, v9
	s_waitcnt vmcnt(34)
	v_pk_add_f32 v[8:9], v[16:17], v[52:53]
	s_nop 0
	v_pk_mul_f32 v[12:13], v[4:5], v[8:9] op_sel:[0,1] op_sel_hi:[1,0]
	global_store_dwordx2 v[94:95], v[8:9], off offset:512
	v_pk_fma_f32 v[16:17], v[2:3], v[8:9], v[12:13] neg_lo:[0,0,1] neg_hi:[0,0,1]
	v_pk_fma_f32 v[8:9], v[2:3], v[8:9], v[12:13]
	s_nop 0
	v_mov_b32_e32 v17, v9
	s_waitcnt vmcnt(34)
	v_pk_add_f32 v[8:9], v[16:17], v[54:55]
	s_nop 0
	v_pk_mul_f32 v[12:13], v[4:5], v[8:9] op_sel:[0,1] op_sel_hi:[1,0]
	global_store_dwordx2 v[94:95], v[8:9], off offset:1024
	v_pk_fma_f32 v[16:17], v[2:3], v[8:9], v[12:13] neg_lo:[0,0,1] neg_hi:[0,0,1]
	v_pk_fma_f32 v[8:9], v[2:3], v[8:9], v[12:13]
	s_nop 0
	v_mov_b32_e32 v17, v9
	s_waitcnt vmcnt(34)
	v_pk_add_f32 v[8:9], v[16:17], v[56:57]
	s_nop 0
	v_pk_mul_f32 v[12:13], v[4:5], v[8:9] op_sel:[0,1] op_sel_hi:[1,0]
	global_store_dwordx2 v[94:95], v[8:9], off offset:1536
	v_pk_fma_f32 v[16:17], v[2:3], v[8:9], v[12:13] neg_lo:[0,0,1] neg_hi:[0,0,1]
	v_pk_fma_f32 v[8:9], v[2:3], v[8:9], v[12:13]
	s_nop 0
	v_mov_b32_e32 v17, v9
	s_waitcnt vmcnt(34)
	v_pk_add_f32 v[8:9], v[16:17], v[58:59]
	s_nop 0
	v_pk_mul_f32 v[12:13], v[4:5], v[8:9] op_sel:[0,1] op_sel_hi:[1,0]
	global_store_dwordx2 v[94:95], v[8:9], off offset:2048
	v_pk_fma_f32 v[16:17], v[2:3], v[8:9], v[12:13] neg_lo:[0,0,1] neg_hi:[0,0,1]
	v_pk_fma_f32 v[8:9], v[2:3], v[8:9], v[12:13]
	s_nop 0
	v_mov_b32_e32 v17, v9
	s_waitcnt vmcnt(34)
	v_pk_add_f32 v[8:9], v[16:17], v[60:61]
	s_nop 0
	v_pk_mul_f32 v[12:13], v[4:5], v[8:9] op_sel:[0,1] op_sel_hi:[1,0]
	global_store_dwordx2 v[94:95], v[8:9], off offset:2560
	v_pk_fma_f32 v[16:17], v[2:3], v[8:9], v[12:13] neg_lo:[0,0,1] neg_hi:[0,0,1]
	v_pk_fma_f32 v[8:9], v[2:3], v[8:9], v[12:13]
	s_nop 0
	v_mov_b32_e32 v17, v9
	s_waitcnt vmcnt(34)
	v_pk_add_f32 v[8:9], v[16:17], v[62:63]
	s_nop 0
	v_pk_mul_f32 v[12:13], v[4:5], v[8:9] op_sel:[0,1] op_sel_hi:[1,0]
	global_store_dwordx2 v[94:95], v[8:9], off offset:3072
	v_pk_fma_f32 v[16:17], v[2:3], v[8:9], v[12:13] neg_lo:[0,0,1] neg_hi:[0,0,1]
	v_pk_fma_f32 v[8:9], v[2:3], v[8:9], v[12:13]
	s_nop 0
	v_mov_b32_e32 v17, v9
	s_waitcnt vmcnt(34)
	v_pk_add_f32 v[8:9], v[16:17], v[64:65]
	s_nop 0
	v_pk_mul_f32 v[12:13], v[4:5], v[8:9] op_sel:[0,1] op_sel_hi:[1,0]
	global_store_dwordx2 v[94:95], v[8:9], off offset:3584
	v_pk_fma_f32 v[16:17], v[2:3], v[8:9], v[12:13] neg_lo:[0,0,1] neg_hi:[0,0,1]
	v_pk_fma_f32 v[8:9], v[2:3], v[8:9], v[12:13]
	s_nop 0
	v_mov_b32_e32 v17, v9
	s_waitcnt vmcnt(34)
	v_pk_add_f32 v[8:9], v[16:17], v[66:67]
	s_nop 0
	v_pk_mul_f32 v[12:13], v[4:5], v[8:9] op_sel:[0,1] op_sel_hi:[1,0]
	global_store_dwordx2 v[96:97], v[8:9], off
	v_pk_fma_f32 v[16:17], v[2:3], v[8:9], v[12:13] neg_lo:[0,0,1] neg_hi:[0,0,1]
	v_pk_fma_f32 v[8:9], v[2:3], v[8:9], v[12:13]
	s_nop 0
	v_mov_b32_e32 v17, v9
	s_waitcnt vmcnt(34)
	v_pk_add_f32 v[8:9], v[16:17], v[68:69]
	s_nop 0
	v_pk_mul_f32 v[12:13], v[4:5], v[8:9] op_sel:[0,1] op_sel_hi:[1,0]
	global_store_dwordx2 v[96:97], v[8:9], off offset:512
	v_pk_fma_f32 v[16:17], v[2:3], v[8:9], v[12:13] neg_lo:[0,0,1] neg_hi:[0,0,1]
	v_pk_fma_f32 v[8:9], v[2:3], v[8:9], v[12:13]
	s_nop 0
	v_mov_b32_e32 v17, v9
	s_waitcnt vmcnt(34)
	v_pk_add_f32 v[8:9], v[16:17], v[70:71]
	s_nop 0
	v_pk_mul_f32 v[12:13], v[4:5], v[8:9] op_sel:[0,1] op_sel_hi:[1,0]
	global_store_dwordx2 v[96:97], v[8:9], off offset:1024
	v_pk_fma_f32 v[16:17], v[2:3], v[8:9], v[12:13] neg_lo:[0,0,1] neg_hi:[0,0,1]
	v_pk_fma_f32 v[8:9], v[2:3], v[8:9], v[12:13]
	s_nop 0
	v_mov_b32_e32 v17, v9
	s_waitcnt vmcnt(34)
	v_pk_add_f32 v[8:9], v[16:17], v[72:73]
	s_nop 0
	v_pk_mul_f32 v[12:13], v[4:5], v[8:9] op_sel:[0,1] op_sel_hi:[1,0]
	global_store_dwordx2 v[96:97], v[8:9], off offset:1536
	v_pk_fma_f32 v[16:17], v[2:3], v[8:9], v[12:13] neg_lo:[0,0,1] neg_hi:[0,0,1]
	v_pk_fma_f32 v[8:9], v[2:3], v[8:9], v[12:13]
	s_nop 0
	v_mov_b32_e32 v17, v9
	s_waitcnt vmcnt(34)
	v_pk_add_f32 v[8:9], v[16:17], v[74:75]
	s_nop 0
	v_pk_mul_f32 v[12:13], v[4:5], v[8:9] op_sel:[0,1] op_sel_hi:[1,0]
	global_store_dwordx2 v[96:97], v[8:9], off offset:2048
	v_pk_fma_f32 v[16:17], v[2:3], v[8:9], v[12:13] neg_lo:[0,0,1] neg_hi:[0,0,1]
	v_pk_fma_f32 v[8:9], v[2:3], v[8:9], v[12:13]
	s_nop 0
	v_mov_b32_e32 v17, v9
	s_waitcnt vmcnt(34)
	v_pk_add_f32 v[8:9], v[16:17], v[76:77]
	s_nop 0
	v_pk_mul_f32 v[12:13], v[4:5], v[8:9] op_sel:[0,1] op_sel_hi:[1,0]
	global_store_dwordx2 v[96:97], v[8:9], off offset:2560
	v_pk_fma_f32 v[16:17], v[2:3], v[8:9], v[12:13] neg_lo:[0,0,1] neg_hi:[0,0,1]
	v_pk_fma_f32 v[8:9], v[2:3], v[8:9], v[12:13]
	s_nop 0
	v_mov_b32_e32 v17, v9
	s_waitcnt vmcnt(34)
	v_pk_add_f32 v[8:9], v[16:17], v[78:79]
	s_nop 0
	v_pk_mul_f32 v[12:13], v[4:5], v[8:9] op_sel:[0,1] op_sel_hi:[1,0]
	global_store_dwordx2 v[96:97], v[8:9], off offset:3072
	v_pk_fma_f32 v[16:17], v[2:3], v[8:9], v[12:13] neg_lo:[0,0,1] neg_hi:[0,0,1]
	v_pk_fma_f32 v[8:9], v[2:3], v[8:9], v[12:13]
	s_nop 0
	v_mov_b32_e32 v17, v9
	s_waitcnt vmcnt(34)
	v_pk_add_f32 v[8:9], v[16:17], v[80:81]
	s_nop 0
	v_pk_mul_f32 v[12:13], v[4:5], v[8:9] op_sel:[0,1] op_sel_hi:[1,0]
	global_store_dwordx2 v[96:97], v[8:9], off offset:3584
	v_pk_fma_f32 v[16:17], v[2:3], v[8:9], v[12:13] neg_lo:[0,0,1] neg_hi:[0,0,1]
	v_pk_fma_f32 v[8:9], v[2:3], v[8:9], v[12:13]
	s_nop 0
	v_mov_b32_e32 v17, v9
	s_waitcnt vmcnt(34)
	v_pk_add_f32 v[8:9], v[16:17], v[82:83]
	s_nop 0
	v_pk_mul_f32 v[12:13], v[4:5], v[8:9] op_sel:[0,1] op_sel_hi:[1,0]
	global_store_dwordx2 v[98:99], v[8:9], off
	v_pk_fma_f32 v[16:17], v[2:3], v[8:9], v[12:13] neg_lo:[0,0,1] neg_hi:[0,0,1]
	v_pk_fma_f32 v[8:9], v[2:3], v[8:9], v[12:13]
	s_nop 0
	v_mov_b32_e32 v17, v9
	s_waitcnt vmcnt(34)
	v_pk_add_f32 v[8:9], v[16:17], v[84:85]
	s_nop 0
	v_pk_mul_f32 v[12:13], v[4:5], v[8:9] op_sel:[0,1] op_sel_hi:[1,0]
	global_store_dwordx2 v[98:99], v[8:9], off offset:512
	v_pk_fma_f32 v[16:17], v[2:3], v[8:9], v[12:13] neg_lo:[0,0,1] neg_hi:[0,0,1]
	v_pk_fma_f32 v[8:9], v[2:3], v[8:9], v[12:13]
	s_nop 0
	v_mov_b32_e32 v17, v9
	s_waitcnt vmcnt(34)
	v_pk_add_f32 v[8:9], v[16:17], v[86:87]
	v_readlane_b32 s4, v254, 48
	v_readlane_b32 s3, v252, 59
	s_add_i32 s6, s6, s4
	s_add_i32 s2, s2, s3
	s_cmp_gt_i32 s6, 63
	v_readlane_b32 s5, v254, 49
	s_cbranch_scc0 .LBB0_512
